# MM: adaLN mod prep item rewritten: 64 weight loads hoisted before silu stage + 64 issued as consumed, double-buffered b128 scr reads (on v10)
# baseline (speedup 1.0000x reference)
; #define GAS __attribute__((address_space(1)))
; __device__ void phase_prep(const Params& p, LAS unsigned char* lds) {
;     ...
;         } else if (it < I_MOD) {
;             const int j = it - I_FOUR, l = j / 96, cb = j % 96;
;             for (int i = tid; i < 5 * 1024; i += 512) { const int r = i >> 10, k = i & 1023; const float v = (r < 4) ? p.c[r * 1024 + k] : p.c_ctx[k]; scr[i] = v / (1.f + __expf(-v)); }
;             __syncthreads();
;             const int col = cb * 64 + (tid & 63), ks = tid >> 6;
;             GAS const float* wm = (GAS const float*)(unsigned long long)p.w_mod + (size_t)l * 1024 * 6144 + col;
;             float a0 = 0.f, a1 = 0.f, a2 = 0.f, a3 = 0.f, a4 = 0.f;
; #pragma unroll 1
;             for (int k0 = ks * 128; k0 < ks * 128 + 128; k0 += 32) {
;                 float wv[32];
; #pragma unroll
;                 for (int q = 0; q < 32; ++q) wv[q] = wm[(size_t)(k0 + q) * 6144];
.LBB0_653:
	s_cmpk_gt_i32 s17, 0x6ff
	s_mov_b64 s[0:1], -1
	s_cbranch_scc0 .LBB0_701
	s_cmpk_gt_u32 s17, 0x77f
	s_cbranch_scc0 .LBB0_696
	s_cmpk_gt_u32 s17, 0x87f
	s_cbranch_scc0 .LBB0_689
	s_cmpk_eq_i32 s17, 0x940
	s_cbranch_scc1 .LBB0_665
	s_add_i32 s18, s17, 0xfffff780
	s_add_i32 s19, s17, 0xfffff720
	s_cmpk_lt_u32 s18, 0x60
	s_cselect_b32 s19, s18, s19
	s_cselect_b32 s18, 0, 0x1800000
	s_lshl_b32 s19, s19, 6
	v_or_b32_e32 v106, s19, v28
	v_mov_b32_e32 v107, 0
	v_mov_b32_e32 v2, s18
	v_mov_b32_e32 v3, 0
	v_lshl_add_u64 v[106:107], v[106:107], 2, v[2:3]
	v_lshl_add_u64 v[106:107], v[46:47], 0, v[106:107]
	v_add_co_u32_e32 v106, vcc, 0xfff46000, v106
	s_nop 1
	v_addc_co_u32_e32 v107, vcc, -1, v107, vcc
	s_mov_b64 s[18:19], 0x6000
	global_load_dword v118, v[106:107], off
	v_lshl_add_u64 v[106:107], v[106:107], 0, s[18:19]
	global_load_dword v119, v[106:107], off
	v_lshl_add_u64 v[106:107], v[106:107], 0, s[18:19]
	global_load_dword v120, v[106:107], off
	v_lshl_add_u64 v[106:107], v[106:107], 0, s[18:19]
	global_load_dword v121, v[106:107], off
	v_lshl_add_u64 v[106:107], v[106:107], 0, s[18:19]
	global_load_dword v122, v[106:107], off
	v_lshl_add_u64 v[106:107], v[106:107], 0, s[18:19]
	global_load_dword v123, v[106:107], off
	v_lshl_add_u64 v[106:107], v[106:107], 0, s[18:19]
	global_load_dword v124, v[106:107], off
	v_lshl_add_u64 v[106:107], v[106:107], 0, s[18:19]
	global_load_dword v125, v[106:107], off
	v_lshl_add_u64 v[106:107], v[106:107], 0, s[18:19]
	global_load_dword v126, v[106:107], off
	v_lshl_add_u64 v[106:107], v[106:107], 0, s[18:19]
	global_load_dword v127, v[106:107], off
	v_lshl_add_u64 v[106:107], v[106:107], 0, s[18:19]
	global_load_dword v128, v[106:107], off
	v_lshl_add_u64 v[106:107], v[106:107], 0, s[18:19]
	global_load_dword v129, v[106:107], off
	v_lshl_add_u64 v[106:107], v[106:107], 0, s[18:19]
	global_load_dword v130, v[106:107], off
	v_lshl_add_u64 v[106:107], v[106:107], 0, s[18:19]
	global_load_dword v131, v[106:107], off
	v_lshl_add_u64 v[106:107], v[106:107], 0, s[18:19]
	global_load_dword v132, v[106:107], off
	v_lshl_add_u64 v[106:107], v[106:107], 0, s[18:19]
	global_load_dword v133, v[106:107], off
	v_lshl_add_u64 v[106:107], v[106:107], 0, s[18:19]
	global_load_dword v134, v[106:107], off
	v_lshl_add_u64 v[106:107], v[106:107], 0, s[18:19]
	global_load_dword v135, v[106:107], off
	v_lshl_add_u64 v[106:107], v[106:107], 0, s[18:19]
	global_load_dword v136, v[106:107], off
	v_lshl_add_u64 v[106:107], v[106:107], 0, s[18:19]
	global_load_dword v137, v[106:107], off
	v_lshl_add_u64 v[106:107], v[106:107], 0, s[18:19]
	global_load_dword v138, v[106:107], off
	v_lshl_add_u64 v[106:107], v[106:107], 0, s[18:19]
	global_load_dword v139, v[106:107], off
	v_lshl_add_u64 v[106:107], v[106:107], 0, s[18:19]
	global_load_dword v140, v[106:107], off
	v_lshl_add_u64 v[106:107], v[106:107], 0, s[18:19]
	global_load_dword v141, v[106:107], off
	v_lshl_add_u64 v[106:107], v[106:107], 0, s[18:19]
	global_load_dword v142, v[106:107], off
	v_lshl_add_u64 v[106:107], v[106:107], 0, s[18:19]
	global_load_dword v143, v[106:107], off
	v_lshl_add_u64 v[106:107], v[106:107], 0, s[18:19]
	global_load_dword v144, v[106:107], off
	v_lshl_add_u64 v[106:107], v[106:107], 0, s[18:19]
	global_load_dword v145, v[106:107], off
	v_lshl_add_u64 v[106:107], v[106:107], 0, s[18:19]
	global_load_dword v146, v[106:107], off
	v_lshl_add_u64 v[106:107], v[106:107], 0, s[18:19]
	global_load_dword v147, v[106:107], off
	v_lshl_add_u64 v[106:107], v[106:107], 0, s[18:19]
	global_load_dword v148, v[106:107], off
	v_lshl_add_u64 v[106:107], v[106:107], 0, s[18:19]
	global_load_dword v149, v[106:107], off
	v_lshl_add_u64 v[106:107], v[106:107], 0, s[18:19]
	global_load_dword v150, v[106:107], off
	v_lshl_add_u64 v[106:107], v[106:107], 0, s[18:19]
	global_load_dword v151, v[106:107], off
	v_lshl_add_u64 v[106:107], v[106:107], 0, s[18:19]
	global_load_dword v152, v[106:107], off
	v_lshl_add_u64 v[106:107], v[106:107], 0, s[18:19]
	global_load_dword v153, v[106:107], off
	v_lshl_add_u64 v[106:107], v[106:107], 0, s[18:19]
	global_load_dword v154, v[106:107], off
	v_lshl_add_u64 v[106:107], v[106:107], 0, s[18:19]
	global_load_dword v155, v[106:107], off
	v_lshl_add_u64 v[106:107], v[106:107], 0, s[18:19]
	global_load_dword v156, v[106:107], off
	v_lshl_add_u64 v[106:107], v[106:107], 0, s[18:19]
	global_load_dword v157, v[106:107], off
	v_lshl_add_u64 v[106:107], v[106:107], 0, s[18:19]
	global_load_dword v158, v[106:107], off
	v_lshl_add_u64 v[106:107], v[106:107], 0, s[18:19]
	global_load_dword v159, v[106:107], off
	v_lshl_add_u64 v[106:107], v[106:107], 0, s[18:19]
	global_load_dword v160, v[106:107], off
	v_lshl_add_u64 v[106:107], v[106:107], 0, s[18:19]
	global_load_dword v161, v[106:107], off
	v_lshl_add_u64 v[106:107], v[106:107], 0, s[18:19]
	global_load_dword v162, v[106:107], off
	v_lshl_add_u64 v[106:107], v[106:107], 0, s[18:19]
	global_load_dword v163, v[106:107], off
	v_lshl_add_u64 v[106:107], v[106:107], 0, s[18:19]
	global_load_dword v164, v[106:107], off
	v_lshl_add_u64 v[106:107], v[106:107], 0, s[18:19]
	global_load_dword v165, v[106:107], off
	v_lshl_add_u64 v[106:107], v[106:107], 0, s[18:19]
	global_load_dword v166, v[106:107], off
	v_lshl_add_u64 v[106:107], v[106:107], 0, s[18:19]
	global_load_dword v167, v[106:107], off
	v_lshl_add_u64 v[106:107], v[106:107], 0, s[18:19]
	global_load_dword v168, v[106:107], off
	v_lshl_add_u64 v[106:107], v[106:107], 0, s[18:19]
	global_load_dword v169, v[106:107], off
	v_lshl_add_u64 v[106:107], v[106:107], 0, s[18:19]
	global_load_dword v170, v[106:107], off
	v_lshl_add_u64 v[106:107], v[106:107], 0, s[18:19]
	global_load_dword v171, v[106:107], off
	v_lshl_add_u64 v[106:107], v[106:107], 0, s[18:19]
	global_load_dword v172, v[106:107], off
	v_lshl_add_u64 v[106:107], v[106:107], 0, s[18:19]
	global_load_dword v173, v[106:107], off
	v_lshl_add_u64 v[106:107], v[106:107], 0, s[18:19]
	global_load_dword v64, v[106:107], off
	v_lshl_add_u64 v[106:107], v[106:107], 0, s[18:19]
	global_load_dword v66, v[106:107], off
	v_lshl_add_u64 v[106:107], v[106:107], 0, s[18:19]
	global_load_dword v67, v[106:107], off
	v_lshl_add_u64 v[106:107], v[106:107], 0, s[18:19]
	global_load_dword v68, v[106:107], off
	v_lshl_add_u64 v[106:107], v[106:107], 0, s[18:19]
	global_load_dword v70, v[106:107], off
	v_lshl_add_u64 v[106:107], v[106:107], 0, s[18:19]
	global_load_dword v72, v[106:107], off
	v_lshl_add_u64 v[106:107], v[106:107], 0, s[18:19]
	global_load_dword v74, v[106:107], off
	v_lshl_add_u64 v[106:107], v[106:107], 0, s[18:19]
	global_load_dword v76, v[106:107], off
	v_lshl_add_u64 v[106:107], v[106:107], 0, s[18:19]
	s_and_saveexec_b64 s[0:1], s[40:41]
	s_cbranch_execz .LBB0_660
	s_mov_b64 s[4:5], 0
	v_mov_b64_e32 v[2:3], v[44:45]
	v_mov_b32_e32 v4, v69
	v_mov_b32_e32 v5, v26

; __device__ void phase_prep(const Params& p, LAS unsigned char* lds) {
;     ...
;             for (int k0 = ks * 128; k0 < ks * 128 + 128; k0 += 32) {
;                 float wv[32];
; #pragma unroll
;                 for (int q = 0; q < 32; ++q) wv[q] = wm[(size_t)(k0 + q) * 6144];
;                 asm volatile("" ::: "memory");
; #pragma unroll
;                 for (int q = 0; q < 32; ++q) { const int k = k0 + q; const float w = wv[q];
;                     a0 += scr[k] * w; a1 += scr[1024 + k] * w; a2 += scr[2048 + k] * w; a3 += scr[3072 + k] * w; a4 += scr[4096 + k] * w; }
.LBB0_661:
	s_mov_b64 s[18:19], 0x6000
	v_mov_b32_e32 v94, 0
	v_mov_b32_e32 v95, 0
	v_mov_b32_e32 v96, 0
	v_mov_b32_e32 v62, 0
	v_mov_b32_e32 v63, 0
	ds_read_b128 v[78:81], v116 offset:0
	ds_read_b128 v[82:85], v116 offset:4096
	ds_read_b128 v[86:89], v116 offset:8192
	ds_read_b128 v[90:93], v116 offset:12288
	ds_read_b128 v[50:53], v116 offset:16384
	ds_read_b128 v[54:57], v116 offset:16
	ds_read_b128 v[58:61], v116 offset:4112
	ds_read_b128 v[2:5], v116 offset:8208
	ds_read_b128 v[98:101], v116 offset:12304
	ds_read_b128 v[102:105], v116 offset:16400
	s_waitcnt lgkmcnt(5)
	v_fmac_f32_e32 v94, v78, v118
	v_fmac_f32_e32 v95, v82, v118
	v_fmac_f32_e32 v96, v86, v118
	v_fmac_f32_e32 v62, v90, v118
	v_fmac_f32_e32 v63, v50, v118
	v_fmac_f32_e32 v94, v79, v119
	v_fmac_f32_e32 v95, v83, v119
	v_fmac_f32_e32 v96, v87, v119
	v_fmac_f32_e32 v62, v91, v119
	v_fmac_f32_e32 v63, v51, v119
	v_fmac_f32_e32 v94, v80, v120
	v_fmac_f32_e32 v95, v84, v120
	v_fmac_f32_e32 v96, v88, v120
	v_fmac_f32_e32 v62, v92, v120
	v_fmac_f32_e32 v63, v52, v120
	v_fmac_f32_e32 v94, v81, v121
	v_fmac_f32_e32 v95, v85, v121
	v_fmac_f32_e32 v96, v89, v121
	v_fmac_f32_e32 v62, v93, v121
	v_fmac_f32_e32 v63, v53, v121
	ds_read_b128 v[78:81], v116 offset:32
	ds_read_b128 v[82:85], v116 offset:4128
	ds_read_b128 v[86:89], v116 offset:8224
	ds_read_b128 v[90:93], v116 offset:12320
	ds_read_b128 v[50:53], v116 offset:16416
	s_waitcnt lgkmcnt(5)
	v_fmac_f32_e32 v94, v54, v122
	v_fmac_f32_e32 v95, v58, v122
	v_fmac_f32_e32 v96, v2, v122
	v_fmac_f32_e32 v62, v98, v122
	v_fmac_f32_e32 v63, v102, v122
	v_fmac_f32_e32 v94, v55, v123
	v_fmac_f32_e32 v95, v59, v123
	v_fmac_f32_e32 v96, v3, v123
	v_fmac_f32_e32 v62, v99, v123
	v_fmac_f32_e32 v63, v103, v123
	v_fmac_f32_e32 v94, v56, v124
	v_fmac_f32_e32 v95, v60, v124
	v_fmac_f32_e32 v96, v4, v124
	v_fmac_f32_e32 v62, v100, v124
	v_fmac_f32_e32 v63, v104, v124
	v_fmac_f32_e32 v94, v57, v125
	v_fmac_f32_e32 v95, v61, v125
	v_fmac_f32_e32 v96, v5, v125
	v_fmac_f32_e32 v62, v101, v125
	v_fmac_f32_e32 v63, v105, v125
	global_load_dword v118, v[106:107], off
	v_lshl_add_u64 v[106:107], v[106:107], 0, s[18:19]
	global_load_dword v119, v[106:107], off
	v_lshl_add_u64 v[106:107], v[106:107], 0, s[18:19]
	global_load_dword v120, v[106:107], off
	v_lshl_add_u64 v[106:107], v[106:107], 0, s[18:19]
	global_load_dword v121, v[106:107], off
	v_lshl_add_u64 v[106:107], v[106:107], 0, s[18:19]
	global_load_dword v122, v[106:107], off
	v_lshl_add_u64 v[106:107], v[106:107], 0, s[18:19]
	global_load_dword v123, v[106:107], off
	v_lshl_add_u64 v[106:107], v[106:107], 0, s[18:19]
	global_load_dword v124, v[106:107], off
	v_lshl_add_u64 v[106:107], v[106:107], 0, s[18:19]
	global_load_dword v125, v[106:107], off
	v_lshl_add_u64 v[106:107], v[106:107], 0, s[18:19]
	ds_read_b128 v[54:57], v116 offset:48
	ds_read_b128 v[58:61], v116 offset:4144
	ds_read_b128 v[2:5], v116 offset:8240
	ds_read_b128 v[98:101], v116 offset:12336
	ds_read_b128 v[102:105], v116 offset:16432
	s_waitcnt lgkmcnt(5)
	v_fmac_f32_e32 v94, v78, v126
	v_fmac_f32_e32 v95, v82, v126
	v_fmac_f32_e32 v96, v86, v126
	v_fmac_f32_e32 v62, v90, v126
	v_fmac_f32_e32 v63, v50, v126
	v_fmac_f32_e32 v94, v79, v127
	v_fmac_f32_e32 v95, v83, v127
	v_fmac_f32_e32 v96, v87, v127
	v_fmac_f32_e32 v62, v91, v127
	v_fmac_f32_e32 v63, v51, v127
	v_fmac_f32_e32 v94, v80, v128
	v_fmac_f32_e32 v95, v84, v128
	v_fmac_f32_e32 v96, v88, v128
	v_fmac_f32_e32 v62, v92, v128
	v_fmac_f32_e32 v63, v52, v128
	v_fmac_f32_e32 v94, v81, v129
	v_fmac_f32_e32 v95, v85, v129
	v_fmac_f32_e32 v96, v89, v129
	v_fmac_f32_e32 v62, v93, v129
	v_fmac_f32_e32 v63, v53, v129
	ds_read_b128 v[78:81], v116 offset:64
	ds_read_b128 v[82:85], v116 offset:4160
	ds_read_b128 v[86:89], v116 offset:8256
	ds_read_b128 v[90:93], v116 offset:12352
	ds_read_b128 v[50:53], v116 offset:16448
	s_waitcnt lgkmcnt(5)
	v_fmac_f32_e32 v94, v54, v130
	v_fmac_f32_e32 v95, v58, v130
	v_fmac_f32_e32 v96, v2, v130
	v_fmac_f32_e32 v62, v98, v130
	v_fmac_f32_e32 v63, v102, v130
	v_fmac_f32_e32 v94, v55, v131
	v_fmac_f32_e32 v95, v59, v131
	v_fmac_f32_e32 v96, v3, v131
	v_fmac_f32_e32 v62, v99, v131
	v_fmac_f32_e32 v63, v103, v131
	v_fmac_f32_e32 v94, v56, v132
	v_fmac_f32_e32 v95, v60, v132
	v_fmac_f32_e32 v96, v4, v132
	v_fmac_f32_e32 v62, v100, v132
	v_fmac_f32_e32 v63, v104, v132
	v_fmac_f32_e32 v94, v57, v133
	v_fmac_f32_e32 v95, v61, v133
	v_fmac_f32_e32 v96, v5, v133
	v_fmac_f32_e32 v62, v101, v133
	v_fmac_f32_e32 v63, v105, v133
	global_load_dword v126, v[106:107], off
	v_lshl_add_u64 v[106:107], v[106:107], 0, s[18:19]
	global_load_dword v127, v[106:107], off
	v_lshl_add_u64 v[106:107], v[106:107], 0, s[18:19]
	global_load_dword v128, v[106:107], off
	v_lshl_add_u64 v[106:107], v[106:107], 0, s[18:19]
	global_load_dword v129, v[106:107], off
	v_lshl_add_u64 v[106:107], v[106:107], 0, s[18:19]
	global_load_dword v130, v[106:107], off
	v_lshl_add_u64 v[106:107], v[106:107], 0, s[18:19]
	global_load_dword v131, v[106:107], off
	v_lshl_add_u64 v[106:107], v[106:107], 0, s[18:19]
	global_load_dword v132, v[106:107], off
	v_lshl_add_u64 v[106:107], v[106:107], 0, s[18:19]
	global_load_dword v133, v[106:107], off
	v_lshl_add_u64 v[106:107], v[106:107], 0, s[18:19]
	ds_read_b128 v[54:57], v116 offset:80
	ds_read_b128 v[58:61], v116 offset:4176
	ds_read_b128 v[2:5], v116 offset:8272
	ds_read_b128 v[98:101], v116 offset:12368
	ds_read_b128 v[102:105], v116 offset:16464
	s_waitcnt lgkmcnt(5)
; __device__ void phase_prep(const Params& p, LAS unsigned char* lds) {
;     ...
;             for (int k0 = ks * 128; k0 < ks * 128 + 128; k0 += 32) {
;                 float wv[32];
; #pragma unroll
;                 for (int q = 0; q < 32; ++q) wv[q] = wm[(size_t)(k0 + q) * 6144];
;                 asm volatile("" ::: "memory");
; #pragma unroll
;                 for (int q = 0; q < 32; ++q) { const int k = k0 + q; const float w = wv[q];
;                     a0 += scr[k] * w; a1 += scr[1024 + k] * w; a2 += scr[2048 + k] * w; a3 += scr[3072 + k] * w; a4 += scr[4096 + k] * w; }
	v_fmac_f32_e32 v94, v78, v134
	v_fmac_f32_e32 v95, v82, v134
	v_fmac_f32_e32 v96, v86, v134
	v_fmac_f32_e32 v62, v90, v134
	v_fmac_f32_e32 v63, v50, v134
	v_fmac_f32_e32 v94, v79, v135
	v_fmac_f32_e32 v95, v83, v135
	v_fmac_f32_e32 v96, v87, v135
	v_fmac_f32_e32 v62, v91, v135
	v_fmac_f32_e32 v63, v51, v135
	v_fmac_f32_e32 v94, v80, v136
	v_fmac_f32_e32 v95, v84, v136
	v_fmac_f32_e32 v96, v88, v136
	v_fmac_f32_e32 v62, v92, v136
	v_fmac_f32_e32 v63, v52, v136
	v_fmac_f32_e32 v94, v81, v137
	v_fmac_f32_e32 v95, v85, v137
	v_fmac_f32_e32 v96, v89, v137
	v_fmac_f32_e32 v62, v93, v137
	v_fmac_f32_e32 v63, v53, v137
	ds_read_b128 v[78:81], v116 offset:96
	ds_read_b128 v[82:85], v116 offset:4192
	ds_read_b128 v[86:89], v116 offset:8288
	ds_read_b128 v[90:93], v116 offset:12384
	ds_read_b128 v[50:53], v116 offset:16480
	s_waitcnt lgkmcnt(5)
	v_fmac_f32_e32 v94, v54, v138
	v_fmac_f32_e32 v95, v58, v138
	v_fmac_f32_e32 v96, v2, v138
	v_fmac_f32_e32 v62, v98, v138
	v_fmac_f32_e32 v63, v102, v138
	v_fmac_f32_e32 v94, v55, v139
	v_fmac_f32_e32 v95, v59, v139
	v_fmac_f32_e32 v96, v3, v139
	v_fmac_f32_e32 v62, v99, v139
	v_fmac_f32_e32 v63, v103, v139
	v_fmac_f32_e32 v94, v56, v140
	v_fmac_f32_e32 v95, v60, v140
	v_fmac_f32_e32 v96, v4, v140
	v_fmac_f32_e32 v62, v100, v140
	v_fmac_f32_e32 v63, v104, v140
	v_fmac_f32_e32 v94, v57, v141
	v_fmac_f32_e32 v95, v61, v141
	v_fmac_f32_e32 v96, v5, v141
	v_fmac_f32_e32 v62, v101, v141
	v_fmac_f32_e32 v63, v105, v141
	global_load_dword v134, v[106:107], off
	v_lshl_add_u64 v[106:107], v[106:107], 0, s[18:19]
	global_load_dword v135, v[106:107], off
	v_lshl_add_u64 v[106:107], v[106:107], 0, s[18:19]
	global_load_dword v136, v[106:107], off
	v_lshl_add_u64 v[106:107], v[106:107], 0, s[18:19]
	global_load_dword v137, v[106:107], off
	v_lshl_add_u64 v[106:107], v[106:107], 0, s[18:19]
	global_load_dword v138, v[106:107], off
	v_lshl_add_u64 v[106:107], v[106:107], 0, s[18:19]
	global_load_dword v139, v[106:107], off
	v_lshl_add_u64 v[106:107], v[106:107], 0, s[18:19]
	global_load_dword v140, v[106:107], off
	v_lshl_add_u64 v[106:107], v[106:107], 0, s[18:19]
	global_load_dword v141, v[106:107], off
	v_lshl_add_u64 v[106:107], v[106:107], 0, s[18:19]
	ds_read_b128 v[54:57], v116 offset:112
	ds_read_b128 v[58:61], v116 offset:4208
	ds_read_b128 v[2:5], v116 offset:8304
	ds_read_b128 v[98:101], v116 offset:12400
	ds_read_b128 v[102:105], v116 offset:16496
	s_waitcnt lgkmcnt(5)
	v_fmac_f32_e32 v94, v78, v142
	v_fmac_f32_e32 v95, v82, v142
	v_fmac_f32_e32 v96, v86, v142
	v_fmac_f32_e32 v62, v90, v142
	v_fmac_f32_e32 v63, v50, v142
	v_fmac_f32_e32 v94, v79, v143
	v_fmac_f32_e32 v95, v83, v143
	v_fmac_f32_e32 v96, v87, v143
	v_fmac_f32_e32 v62, v91, v143
	v_fmac_f32_e32 v63, v51, v143
	v_fmac_f32_e32 v94, v80, v144
	v_fmac_f32_e32 v95, v84, v144
	v_fmac_f32_e32 v96, v88, v144
	v_fmac_f32_e32 v62, v92, v144
	v_fmac_f32_e32 v63, v52, v144
	v_fmac_f32_e32 v94, v81, v145
	v_fmac_f32_e32 v95, v85, v145
	v_fmac_f32_e32 v96, v89, v145
	v_fmac_f32_e32 v62, v93, v145
	v_fmac_f32_e32 v63, v53, v145
	ds_read_b128 v[78:81], v116 offset:128
	ds_read_b128 v[82:85], v116 offset:4224
	ds_read_b128 v[86:89], v116 offset:8320
	ds_read_b128 v[90:93], v116 offset:12416
	ds_read_b128 v[50:53], v116 offset:16512
	s_waitcnt lgkmcnt(5)
	v_fmac_f32_e32 v94, v54, v146
	v_fmac_f32_e32 v95, v58, v146
	v_fmac_f32_e32 v96, v2, v146
	v_fmac_f32_e32 v62, v98, v146
	v_fmac_f32_e32 v63, v102, v146
	v_fmac_f32_e32 v94, v55, v147
	v_fmac_f32_e32 v95, v59, v147
	v_fmac_f32_e32 v96, v3, v147
	v_fmac_f32_e32 v62, v99, v147
	v_fmac_f32_e32 v63, v103, v147
	v_fmac_f32_e32 v94, v56, v148
	v_fmac_f32_e32 v95, v60, v148
	v_fmac_f32_e32 v96, v4, v148
	v_fmac_f32_e32 v62, v100, v148
	v_fmac_f32_e32 v63, v104, v148
	v_fmac_f32_e32 v94, v57, v149
	v_fmac_f32_e32 v95, v61, v149
	v_fmac_f32_e32 v96, v5, v149
	v_fmac_f32_e32 v62, v101, v149
	v_fmac_f32_e32 v63, v105, v149
	global_load_dword v142, v[106:107], off
	v_lshl_add_u64 v[106:107], v[106:107], 0, s[18:19]
	global_load_dword v143, v[106:107], off
	v_lshl_add_u64 v[106:107], v[106:107], 0, s[18:19]
	global_load_dword v144, v[106:107], off
	v_lshl_add_u64 v[106:107], v[106:107], 0, s[18:19]
	global_load_dword v145, v[106:107], off
	v_lshl_add_u64 v[106:107], v[106:107], 0, s[18:19]
	global_load_dword v146, v[106:107], off
	v_lshl_add_u64 v[106:107], v[106:107], 0, s[18:19]
	global_load_dword v147, v[106:107], off
	v_lshl_add_u64 v[106:107], v[106:107], 0, s[18:19]
	global_load_dword v148, v[106:107], off
	v_lshl_add_u64 v[106:107], v[106:107], 0, s[18:19]
	global_load_dword v149, v[106:107], off
	v_lshl_add_u64 v[106:107], v[106:107], 0, s[18:19]
	ds_read_b128 v[54:57], v116 offset:144
	ds_read_b128 v[58:61], v116 offset:4240
	ds_read_b128 v[2:5], v116 offset:8336
	ds_read_b128 v[98:101], v116 offset:12432
	ds_read_b128 v[102:105], v116 offset:16528
	s_waitcnt lgkmcnt(5)
	v_fmac_f32_e32 v94, v78, v150
	v_fmac_f32_e32 v95, v82, v150
	v_fmac_f32_e32 v96, v86, v150
	v_fmac_f32_e32 v62, v90, v150
	v_fmac_f32_e32 v63, v50, v150
	v_fmac_f32_e32 v94, v79, v151
	v_fmac_f32_e32 v95, v83, v151
	v_fmac_f32_e32 v96, v87, v151
	v_fmac_f32_e32 v62, v91, v151
	v_fmac_f32_e32 v63, v51, v151
	v_fmac_f32_e32 v94, v80, v152
	v_fmac_f32_e32 v95, v84, v152
	v_fmac_f32_e32 v96, v88, v152
	v_fmac_f32_e32 v62, v92, v152
	v_fmac_f32_e32 v63, v52, v152
	v_fmac_f32_e32 v94, v81, v153
	v_fmac_f32_e32 v95, v85, v153
	v_fmac_f32_e32 v96, v89, v153
	v_fmac_f32_e32 v62, v93, v153
	v_fmac_f32_e32 v63, v53, v153
	ds_read_b128 v[78:81], v116 offset:160
	ds_read_b128 v[82:85], v116 offset:4256
	ds_read_b128 v[86:89], v116 offset:8352
	ds_read_b128 v[90:93], v116 offset:12448
	ds_read_b128 v[50:53], v116 offset:16544
	s_waitcnt lgkmcnt(5)
; __device__ void phase_prep(const Params& p, LAS unsigned char* lds) {
;     ...
;             for (int k0 = ks * 128; k0 < ks * 128 + 128; k0 += 32) {
;                 float wv[32];
; #pragma unroll
;                 for (int q = 0; q < 32; ++q) wv[q] = wm[(size_t)(k0 + q) * 6144];
;                 asm volatile("" ::: "memory");
; #pragma unroll
;                 for (int q = 0; q < 32; ++q) { const int k = k0 + q; const float w = wv[q];
;                     a0 += scr[k] * w; a1 += scr[1024 + k] * w; a2 += scr[2048 + k] * w; a3 += scr[3072 + k] * w; a4 += scr[4096 + k] * w; }
	v_fmac_f32_e32 v94, v54, v154
	v_fmac_f32_e32 v95, v58, v154
	v_fmac_f32_e32 v96, v2, v154
	v_fmac_f32_e32 v62, v98, v154
	v_fmac_f32_e32 v63, v102, v154
	v_fmac_f32_e32 v94, v55, v155
	v_fmac_f32_e32 v95, v59, v155
	v_fmac_f32_e32 v96, v3, v155
	v_fmac_f32_e32 v62, v99, v155
	v_fmac_f32_e32 v63, v103, v155
	v_fmac_f32_e32 v94, v56, v156
	v_fmac_f32_e32 v95, v60, v156
	v_fmac_f32_e32 v96, v4, v156
	v_fmac_f32_e32 v62, v100, v156
	v_fmac_f32_e32 v63, v104, v156
	v_fmac_f32_e32 v94, v57, v157
	v_fmac_f32_e32 v95, v61, v157
	v_fmac_f32_e32 v96, v5, v157
	v_fmac_f32_e32 v62, v101, v157
	v_fmac_f32_e32 v63, v105, v157
	global_load_dword v150, v[106:107], off
	v_lshl_add_u64 v[106:107], v[106:107], 0, s[18:19]
	global_load_dword v151, v[106:107], off
	v_lshl_add_u64 v[106:107], v[106:107], 0, s[18:19]
	global_load_dword v152, v[106:107], off
	v_lshl_add_u64 v[106:107], v[106:107], 0, s[18:19]
	global_load_dword v153, v[106:107], off
	v_lshl_add_u64 v[106:107], v[106:107], 0, s[18:19]
	global_load_dword v154, v[106:107], off
	v_lshl_add_u64 v[106:107], v[106:107], 0, s[18:19]
	global_load_dword v155, v[106:107], off
	v_lshl_add_u64 v[106:107], v[106:107], 0, s[18:19]
	global_load_dword v156, v[106:107], off
	v_lshl_add_u64 v[106:107], v[106:107], 0, s[18:19]
	global_load_dword v157, v[106:107], off
	v_lshl_add_u64 v[106:107], v[106:107], 0, s[18:19]
	ds_read_b128 v[54:57], v116 offset:176
	ds_read_b128 v[58:61], v116 offset:4272
	ds_read_b128 v[2:5], v116 offset:8368
	ds_read_b128 v[98:101], v116 offset:12464
	ds_read_b128 v[102:105], v116 offset:16560
	s_waitcnt lgkmcnt(5)
	v_fmac_f32_e32 v94, v78, v158
	v_fmac_f32_e32 v95, v82, v158
	v_fmac_f32_e32 v96, v86, v158
	v_fmac_f32_e32 v62, v90, v158
	v_fmac_f32_e32 v63, v50, v158
	v_fmac_f32_e32 v94, v79, v159
	v_fmac_f32_e32 v95, v83, v159
	v_fmac_f32_e32 v96, v87, v159
	v_fmac_f32_e32 v62, v91, v159
	v_fmac_f32_e32 v63, v51, v159
	v_fmac_f32_e32 v94, v80, v160
	v_fmac_f32_e32 v95, v84, v160
	v_fmac_f32_e32 v96, v88, v160
	v_fmac_f32_e32 v62, v92, v160
	v_fmac_f32_e32 v63, v52, v160
	v_fmac_f32_e32 v94, v81, v161
	v_fmac_f32_e32 v95, v85, v161
	v_fmac_f32_e32 v96, v89, v161
	v_fmac_f32_e32 v62, v93, v161
	v_fmac_f32_e32 v63, v53, v161
	ds_read_b128 v[78:81], v116 offset:192
	ds_read_b128 v[82:85], v116 offset:4288
	ds_read_b128 v[86:89], v116 offset:8384
	ds_read_b128 v[90:93], v116 offset:12480
	ds_read_b128 v[50:53], v116 offset:16576
	s_waitcnt lgkmcnt(5)
	v_fmac_f32_e32 v94, v54, v162
	v_fmac_f32_e32 v95, v58, v162
	v_fmac_f32_e32 v96, v2, v162
	v_fmac_f32_e32 v62, v98, v162
	v_fmac_f32_e32 v63, v102, v162
	v_fmac_f32_e32 v94, v55, v163
	v_fmac_f32_e32 v95, v59, v163
	v_fmac_f32_e32 v96, v3, v163
	v_fmac_f32_e32 v62, v99, v163
	v_fmac_f32_e32 v63, v103, v163
	v_fmac_f32_e32 v94, v56, v164
	v_fmac_f32_e32 v95, v60, v164
	v_fmac_f32_e32 v96, v4, v164
	v_fmac_f32_e32 v62, v100, v164
	v_fmac_f32_e32 v63, v104, v164
	v_fmac_f32_e32 v94, v57, v165
	v_fmac_f32_e32 v95, v61, v165
	v_fmac_f32_e32 v96, v5, v165
	v_fmac_f32_e32 v62, v101, v165
	v_fmac_f32_e32 v63, v105, v165
	global_load_dword v158, v[106:107], off
	v_lshl_add_u64 v[106:107], v[106:107], 0, s[18:19]
	global_load_dword v159, v[106:107], off
	v_lshl_add_u64 v[106:107], v[106:107], 0, s[18:19]
	global_load_dword v160, v[106:107], off
	v_lshl_add_u64 v[106:107], v[106:107], 0, s[18:19]
	global_load_dword v161, v[106:107], off
	v_lshl_add_u64 v[106:107], v[106:107], 0, s[18:19]
	global_load_dword v162, v[106:107], off
	v_lshl_add_u64 v[106:107], v[106:107], 0, s[18:19]
	global_load_dword v163, v[106:107], off
	v_lshl_add_u64 v[106:107], v[106:107], 0, s[18:19]
	global_load_dword v164, v[106:107], off
	v_lshl_add_u64 v[106:107], v[106:107], 0, s[18:19]
	global_load_dword v165, v[106:107], off
	v_lshl_add_u64 v[106:107], v[106:107], 0, s[18:19]
	ds_read_b128 v[54:57], v116 offset:208
	ds_read_b128 v[58:61], v116 offset:4304
	ds_read_b128 v[2:5], v116 offset:8400
	ds_read_b128 v[98:101], v116 offset:12496
	ds_read_b128 v[102:105], v116 offset:16592
	s_waitcnt lgkmcnt(5)
	v_fmac_f32_e32 v94, v78, v166
	v_fmac_f32_e32 v95, v82, v166
	v_fmac_f32_e32 v96, v86, v166
	v_fmac_f32_e32 v62, v90, v166
	v_fmac_f32_e32 v63, v50, v166
	v_fmac_f32_e32 v94, v79, v167
	v_fmac_f32_e32 v95, v83, v167
	v_fmac_f32_e32 v96, v87, v167
	v_fmac_f32_e32 v62, v91, v167
	v_fmac_f32_e32 v63, v51, v167
	v_fmac_f32_e32 v94, v80, v168
	v_fmac_f32_e32 v95, v84, v168
	v_fmac_f32_e32 v96, v88, v168
	v_fmac_f32_e32 v62, v92, v168
	v_fmac_f32_e32 v63, v52, v168
	v_fmac_f32_e32 v94, v81, v169
	v_fmac_f32_e32 v95, v85, v169
	v_fmac_f32_e32 v96, v89, v169
	v_fmac_f32_e32 v62, v93, v169
	v_fmac_f32_e32 v63, v53, v169
	ds_read_b128 v[78:81], v116 offset:224
	ds_read_b128 v[82:85], v116 offset:4320
	ds_read_b128 v[86:89], v116 offset:8416
	ds_read_b128 v[90:93], v116 offset:12512
	ds_read_b128 v[50:53], v116 offset:16608
	s_waitcnt lgkmcnt(5)
; __device__ void phase_prep(const Params& p, LAS unsigned char* lds) {
;     ...
;             for (int k0 = ks * 128; k0 < ks * 128 + 128; k0 += 32) {
;                 float wv[32];
; #pragma unroll
;                 for (int q = 0; q < 32; ++q) wv[q] = wm[(size_t)(k0 + q) * 6144];
;                 asm volatile("" ::: "memory");
; #pragma unroll
;                 for (int q = 0; q < 32; ++q) { const int k = k0 + q; const float w = wv[q];
;                     a0 += scr[k] * w; a1 += scr[1024 + k] * w; a2 += scr[2048 + k] * w; a3 += scr[3072 + k] * w; a4 += scr[4096 + k] * w; }
	v_fmac_f32_e32 v94, v54, v170
	v_fmac_f32_e32 v95, v58, v170
	v_fmac_f32_e32 v96, v2, v170
	v_fmac_f32_e32 v62, v98, v170
	v_fmac_f32_e32 v63, v102, v170
	v_fmac_f32_e32 v94, v55, v171
	v_fmac_f32_e32 v95, v59, v171
	v_fmac_f32_e32 v96, v3, v171
	v_fmac_f32_e32 v62, v99, v171
	v_fmac_f32_e32 v63, v103, v171
	v_fmac_f32_e32 v94, v56, v172
	v_fmac_f32_e32 v95, v60, v172
	v_fmac_f32_e32 v96, v4, v172
	v_fmac_f32_e32 v62, v100, v172
	v_fmac_f32_e32 v63, v104, v172
	v_fmac_f32_e32 v94, v57, v173
	v_fmac_f32_e32 v95, v61, v173
	v_fmac_f32_e32 v96, v5, v173
	v_fmac_f32_e32 v62, v101, v173
	v_fmac_f32_e32 v63, v105, v173
	global_load_dword v166, v[106:107], off
	v_lshl_add_u64 v[106:107], v[106:107], 0, s[18:19]
	global_load_dword v167, v[106:107], off
	v_lshl_add_u64 v[106:107], v[106:107], 0, s[18:19]
	global_load_dword v168, v[106:107], off
	v_lshl_add_u64 v[106:107], v[106:107], 0, s[18:19]
	global_load_dword v169, v[106:107], off
	v_lshl_add_u64 v[106:107], v[106:107], 0, s[18:19]
	global_load_dword v170, v[106:107], off
	v_lshl_add_u64 v[106:107], v[106:107], 0, s[18:19]
	global_load_dword v171, v[106:107], off
	v_lshl_add_u64 v[106:107], v[106:107], 0, s[18:19]
	global_load_dword v172, v[106:107], off
	v_lshl_add_u64 v[106:107], v[106:107], 0, s[18:19]
	global_load_dword v173, v[106:107], off
	v_lshl_add_u64 v[106:107], v[106:107], 0, s[18:19]
	ds_read_b128 v[54:57], v116 offset:240
	ds_read_b128 v[58:61], v116 offset:4336
	ds_read_b128 v[2:5], v116 offset:8432
	ds_read_b128 v[98:101], v116 offset:12528
	ds_read_b128 v[102:105], v116 offset:16624
	s_waitcnt lgkmcnt(5)
	v_fmac_f32_e32 v94, v78, v64
	v_fmac_f32_e32 v95, v82, v64
	v_fmac_f32_e32 v96, v86, v64
	v_fmac_f32_e32 v62, v90, v64
	v_fmac_f32_e32 v63, v50, v64
	v_fmac_f32_e32 v94, v79, v66
	v_fmac_f32_e32 v95, v83, v66
	v_fmac_f32_e32 v96, v87, v66
	v_fmac_f32_e32 v62, v91, v66
	v_fmac_f32_e32 v63, v51, v66
	v_fmac_f32_e32 v94, v80, v67
	v_fmac_f32_e32 v95, v84, v67
	v_fmac_f32_e32 v96, v88, v67
	v_fmac_f32_e32 v62, v92, v67
	v_fmac_f32_e32 v63, v52, v67
	v_fmac_f32_e32 v94, v81, v68
	v_fmac_f32_e32 v95, v85, v68
	v_fmac_f32_e32 v96, v89, v68
	v_fmac_f32_e32 v62, v93, v68
	v_fmac_f32_e32 v63, v53, v68
	ds_read_b128 v[78:81], v116 offset:256
	ds_read_b128 v[82:85], v116 offset:4352
	ds_read_b128 v[86:89], v116 offset:8448
	ds_read_b128 v[90:93], v116 offset:12544
	ds_read_b128 v[50:53], v116 offset:16640
	s_waitcnt lgkmcnt(5)
	v_fmac_f32_e32 v94, v54, v70
	v_fmac_f32_e32 v95, v58, v70
	v_fmac_f32_e32 v96, v2, v70
	v_fmac_f32_e32 v62, v98, v70
	v_fmac_f32_e32 v63, v102, v70
	v_fmac_f32_e32 v94, v55, v72
	v_fmac_f32_e32 v95, v59, v72
	v_fmac_f32_e32 v96, v3, v72
	v_fmac_f32_e32 v62, v99, v72
	v_fmac_f32_e32 v63, v103, v72
	v_fmac_f32_e32 v94, v56, v74
	v_fmac_f32_e32 v95, v60, v74
	v_fmac_f32_e32 v96, v4, v74
	v_fmac_f32_e32 v62, v100, v74
	v_fmac_f32_e32 v63, v104, v74
	v_fmac_f32_e32 v94, v57, v76
	v_fmac_f32_e32 v95, v61, v76
	v_fmac_f32_e32 v96, v5, v76
	v_fmac_f32_e32 v62, v101, v76
	v_fmac_f32_e32 v63, v105, v76
	global_load_dword v64, v[106:107], off
	v_lshl_add_u64 v[106:107], v[106:107], 0, s[18:19]
	global_load_dword v66, v[106:107], off
	v_lshl_add_u64 v[106:107], v[106:107], 0, s[18:19]
	global_load_dword v67, v[106:107], off
	v_lshl_add_u64 v[106:107], v[106:107], 0, s[18:19]
	global_load_dword v68, v[106:107], off
	v_lshl_add_u64 v[106:107], v[106:107], 0, s[18:19]
	global_load_dword v70, v[106:107], off
	v_lshl_add_u64 v[106:107], v[106:107], 0, s[18:19]
	global_load_dword v72, v[106:107], off
	v_lshl_add_u64 v[106:107], v[106:107], 0, s[18:19]
	global_load_dword v74, v[106:107], off
	v_lshl_add_u64 v[106:107], v[106:107], 0, s[18:19]
	global_load_dword v76, v[106:107], off
	v_lshl_add_u64 v[106:107], v[106:107], 0, s[18:19]
	ds_read_b128 v[54:57], v116 offset:272
	ds_read_b128 v[58:61], v116 offset:4368
	ds_read_b128 v[2:5], v116 offset:8464
	ds_read_b128 v[98:101], v116 offset:12560
	ds_read_b128 v[102:105], v116 offset:16656
	s_waitcnt vmcnt(56) lgkmcnt(5)
	v_fmac_f32_e32 v94, v78, v118
	v_fmac_f32_e32 v95, v82, v118
	v_fmac_f32_e32 v96, v86, v118
	v_fmac_f32_e32 v62, v90, v118
	v_fmac_f32_e32 v63, v50, v118
	v_fmac_f32_e32 v94, v79, v119
	v_fmac_f32_e32 v95, v83, v119
	v_fmac_f32_e32 v96, v87, v119
	v_fmac_f32_e32 v62, v91, v119
	v_fmac_f32_e32 v63, v51, v119
	v_fmac_f32_e32 v94, v80, v120
	v_fmac_f32_e32 v95, v84, v120
	v_fmac_f32_e32 v96, v88, v120
	v_fmac_f32_e32 v62, v92, v120
	v_fmac_f32_e32 v63, v52, v120
	v_fmac_f32_e32 v94, v81, v121
	v_fmac_f32_e32 v95, v85, v121
	v_fmac_f32_e32 v96, v89, v121
	v_fmac_f32_e32 v62, v93, v121
	v_fmac_f32_e32 v63, v53, v121
	ds_read_b128 v[78:81], v116 offset:288
	ds_read_b128 v[82:85], v116 offset:4384
	ds_read_b128 v[86:89], v116 offset:8480
	ds_read_b128 v[90:93], v116 offset:12576
	ds_read_b128 v[50:53], v116 offset:16672
	s_waitcnt lgkmcnt(5)
	v_fmac_f32_e32 v94, v54, v122
	v_fmac_f32_e32 v95, v58, v122
	v_fmac_f32_e32 v96, v2, v122
	v_fmac_f32_e32 v62, v98, v122
	v_fmac_f32_e32 v63, v102, v122
	v_fmac_f32_e32 v94, v55, v123
	v_fmac_f32_e32 v95, v59, v123
	v_fmac_f32_e32 v96, v3, v123
	v_fmac_f32_e32 v62, v99, v123
	v_fmac_f32_e32 v63, v103, v123
	v_fmac_f32_e32 v94, v56, v124
	v_fmac_f32_e32 v95, v60, v124
	v_fmac_f32_e32 v96, v4, v124
	v_fmac_f32_e32 v62, v100, v124
	v_fmac_f32_e32 v63, v104, v124
	v_fmac_f32_e32 v94, v57, v125
	v_fmac_f32_e32 v95, v61, v125
	v_fmac_f32_e32 v96, v5, v125
	v_fmac_f32_e32 v62, v101, v125
	v_fmac_f32_e32 v63, v105, v125
	ds_read_b128 v[54:57], v116 offset:304
	ds_read_b128 v[58:61], v116 offset:4400
	ds_read_b128 v[2:5], v116 offset:8496
	ds_read_b128 v[98:101], v116 offset:12592
	ds_read_b128 v[102:105], v116 offset:16688
	s_waitcnt vmcnt(48) lgkmcnt(5)
; __device__ void phase_prep(const Params& p, LAS unsigned char* lds) {
;     ...
;             for (int k0 = ks * 128; k0 < ks * 128 + 128; k0 += 32) {
;                 float wv[32];
; #pragma unroll
;                 for (int q = 0; q < 32; ++q) wv[q] = wm[(size_t)(k0 + q) * 6144];
;                 asm volatile("" ::: "memory");
; #pragma unroll
;                 for (int q = 0; q < 32; ++q) { const int k = k0 + q; const float w = wv[q];
;                     a0 += scr[k] * w; a1 += scr[1024 + k] * w; a2 += scr[2048 + k] * w; a3 += scr[3072 + k] * w; a4 += scr[4096 + k] * w; }
	v_fmac_f32_e32 v94, v78, v126
	v_fmac_f32_e32 v95, v82, v126
	v_fmac_f32_e32 v96, v86, v126
	v_fmac_f32_e32 v62, v90, v126
	v_fmac_f32_e32 v63, v50, v126
	v_fmac_f32_e32 v94, v79, v127
	v_fmac_f32_e32 v95, v83, v127
	v_fmac_f32_e32 v96, v87, v127
	v_fmac_f32_e32 v62, v91, v127
	v_fmac_f32_e32 v63, v51, v127
	v_fmac_f32_e32 v94, v80, v128
	v_fmac_f32_e32 v95, v84, v128
	v_fmac_f32_e32 v96, v88, v128
	v_fmac_f32_e32 v62, v92, v128
	v_fmac_f32_e32 v63, v52, v128
	v_fmac_f32_e32 v94, v81, v129
	v_fmac_f32_e32 v95, v85, v129
	v_fmac_f32_e32 v96, v89, v129
	v_fmac_f32_e32 v62, v93, v129
	v_fmac_f32_e32 v63, v53, v129
	ds_read_b128 v[78:81], v116 offset:320
	ds_read_b128 v[82:85], v116 offset:4416
	ds_read_b128 v[86:89], v116 offset:8512
	ds_read_b128 v[90:93], v116 offset:12608
	ds_read_b128 v[50:53], v116 offset:16704
	s_waitcnt lgkmcnt(5)
	v_fmac_f32_e32 v94, v54, v130
	v_fmac_f32_e32 v95, v58, v130
	v_fmac_f32_e32 v96, v2, v130
	v_fmac_f32_e32 v62, v98, v130
	v_fmac_f32_e32 v63, v102, v130
	v_fmac_f32_e32 v94, v55, v131
	v_fmac_f32_e32 v95, v59, v131
	v_fmac_f32_e32 v96, v3, v131
	v_fmac_f32_e32 v62, v99, v131
	v_fmac_f32_e32 v63, v103, v131
	v_fmac_f32_e32 v94, v56, v132
	v_fmac_f32_e32 v95, v60, v132
	v_fmac_f32_e32 v96, v4, v132
	v_fmac_f32_e32 v62, v100, v132
	v_fmac_f32_e32 v63, v104, v132
	v_fmac_f32_e32 v94, v57, v133
	v_fmac_f32_e32 v95, v61, v133
	v_fmac_f32_e32 v96, v5, v133
	v_fmac_f32_e32 v62, v101, v133
	v_fmac_f32_e32 v63, v105, v133
	ds_read_b128 v[54:57], v116 offset:336
	ds_read_b128 v[58:61], v116 offset:4432
	ds_read_b128 v[2:5], v116 offset:8528
	ds_read_b128 v[98:101], v116 offset:12624
	ds_read_b128 v[102:105], v116 offset:16720
	s_waitcnt vmcnt(40) lgkmcnt(5)
	v_fmac_f32_e32 v94, v78, v134
	v_fmac_f32_e32 v95, v82, v134
	v_fmac_f32_e32 v96, v86, v134
	v_fmac_f32_e32 v62, v90, v134
	v_fmac_f32_e32 v63, v50, v134
	v_fmac_f32_e32 v94, v79, v135
	v_fmac_f32_e32 v95, v83, v135
	v_fmac_f32_e32 v96, v87, v135
	v_fmac_f32_e32 v62, v91, v135
	v_fmac_f32_e32 v63, v51, v135
	v_fmac_f32_e32 v94, v80, v136
	v_fmac_f32_e32 v95, v84, v136
	v_fmac_f32_e32 v96, v88, v136
	v_fmac_f32_e32 v62, v92, v136
	v_fmac_f32_e32 v63, v52, v136
	v_fmac_f32_e32 v94, v81, v137
	v_fmac_f32_e32 v95, v85, v137
	v_fmac_f32_e32 v96, v89, v137
	v_fmac_f32_e32 v62, v93, v137
	v_fmac_f32_e32 v63, v53, v137
	ds_read_b128 v[78:81], v116 offset:352
	ds_read_b128 v[82:85], v116 offset:4448
	ds_read_b128 v[86:89], v116 offset:8544
	ds_read_b128 v[90:93], v116 offset:12640
	ds_read_b128 v[50:53], v116 offset:16736
	s_waitcnt lgkmcnt(5)
	v_fmac_f32_e32 v94, v54, v138
	v_fmac_f32_e32 v95, v58, v138
	v_fmac_f32_e32 v96, v2, v138
	v_fmac_f32_e32 v62, v98, v138
	v_fmac_f32_e32 v63, v102, v138
	v_fmac_f32_e32 v94, v55, v139
	v_fmac_f32_e32 v95, v59, v139
	v_fmac_f32_e32 v96, v3, v139
	v_fmac_f32_e32 v62, v99, v139
	v_fmac_f32_e32 v63, v103, v139
	v_fmac_f32_e32 v94, v56, v140
	v_fmac_f32_e32 v95, v60, v140
	v_fmac_f32_e32 v96, v4, v140
	v_fmac_f32_e32 v62, v100, v140
	v_fmac_f32_e32 v63, v104, v140
	v_fmac_f32_e32 v94, v57, v141
	v_fmac_f32_e32 v95, v61, v141
	v_fmac_f32_e32 v96, v5, v141
	v_fmac_f32_e32 v62, v101, v141
	v_fmac_f32_e32 v63, v105, v141
	ds_read_b128 v[54:57], v116 offset:368
	ds_read_b128 v[58:61], v116 offset:4464
	ds_read_b128 v[2:5], v116 offset:8560
	ds_read_b128 v[98:101], v116 offset:12656
	ds_read_b128 v[102:105], v116 offset:16752
	s_waitcnt vmcnt(32) lgkmcnt(5)
	v_fmac_f32_e32 v94, v78, v142
	v_fmac_f32_e32 v95, v82, v142
	v_fmac_f32_e32 v96, v86, v142
	v_fmac_f32_e32 v62, v90, v142
	v_fmac_f32_e32 v63, v50, v142
	v_fmac_f32_e32 v94, v79, v143
	v_fmac_f32_e32 v95, v83, v143
	v_fmac_f32_e32 v96, v87, v143
	v_fmac_f32_e32 v62, v91, v143
	v_fmac_f32_e32 v63, v51, v143
	v_fmac_f32_e32 v94, v80, v144
	v_fmac_f32_e32 v95, v84, v144
	v_fmac_f32_e32 v96, v88, v144
	v_fmac_f32_e32 v62, v92, v144
	v_fmac_f32_e32 v63, v52, v144
	v_fmac_f32_e32 v94, v81, v145
	v_fmac_f32_e32 v95, v85, v145
	v_fmac_f32_e32 v96, v89, v145
	v_fmac_f32_e32 v62, v93, v145
	v_fmac_f32_e32 v63, v53, v145
	ds_read_b128 v[78:81], v116 offset:384
	ds_read_b128 v[82:85], v116 offset:4480
	ds_read_b128 v[86:89], v116 offset:8576
	ds_read_b128 v[90:93], v116 offset:12672
	ds_read_b128 v[50:53], v116 offset:16768
	s_waitcnt lgkmcnt(5)
	v_fmac_f32_e32 v94, v54, v146
	v_fmac_f32_e32 v95, v58, v146
	v_fmac_f32_e32 v96, v2, v146
	v_fmac_f32_e32 v62, v98, v146
	v_fmac_f32_e32 v63, v102, v146
	v_fmac_f32_e32 v94, v55, v147
	v_fmac_f32_e32 v95, v59, v147
	v_fmac_f32_e32 v96, v3, v147
	v_fmac_f32_e32 v62, v99, v147
	v_fmac_f32_e32 v63, v103, v147
	v_fmac_f32_e32 v94, v56, v148
	v_fmac_f32_e32 v95, v60, v148
	v_fmac_f32_e32 v96, v4, v148
	v_fmac_f32_e32 v62, v100, v148
	v_fmac_f32_e32 v63, v104, v148
	v_fmac_f32_e32 v94, v57, v149
	v_fmac_f32_e32 v95, v61, v149
	v_fmac_f32_e32 v96, v5, v149
	v_fmac_f32_e32 v62, v101, v149
	v_fmac_f32_e32 v63, v105, v149
	ds_read_b128 v[54:57], v116 offset:400
	ds_read_b128 v[58:61], v116 offset:4496
	ds_read_b128 v[2:5], v116 offset:8592
	ds_read_b128 v[98:101], v116 offset:12688
	ds_read_b128 v[102:105], v116 offset:16784
	s_waitcnt vmcnt(24) lgkmcnt(5)
	v_fmac_f32_e32 v94, v78, v150
	v_fmac_f32_e32 v95, v82, v150
	v_fmac_f32_e32 v96, v86, v150
	v_fmac_f32_e32 v62, v90, v150
	v_fmac_f32_e32 v63, v50, v150
	v_fmac_f32_e32 v94, v79, v151
	v_fmac_f32_e32 v95, v83, v151
	v_fmac_f32_e32 v96, v87, v151
	v_fmac_f32_e32 v62, v91, v151
	v_fmac_f32_e32 v63, v51, v151
	v_fmac_f32_e32 v94, v80, v152
	v_fmac_f32_e32 v95, v84, v152
	v_fmac_f32_e32 v96, v88, v152
	v_fmac_f32_e32 v62, v92, v152
	v_fmac_f32_e32 v63, v52, v152
	v_fmac_f32_e32 v94, v81, v153
	v_fmac_f32_e32 v95, v85, v153
	v_fmac_f32_e32 v96, v89, v153
	v_fmac_f32_e32 v62, v93, v153
	v_fmac_f32_e32 v63, v53, v153
	ds_read_b128 v[78:81], v116 offset:416
	ds_read_b128 v[82:85], v116 offset:4512
	ds_read_b128 v[86:89], v116 offset:8608
	ds_read_b128 v[90:93], v116 offset:12704
	ds_read_b128 v[50:53], v116 offset:16800
	s_waitcnt lgkmcnt(5)
; #define LAS __attribute__((address_space(3)))
; __device__ void phase_prep(const Params& p, LAS unsigned char* lds) {
;     ...
;             for (int k0 = ks * 128; k0 < ks * 128 + 128; k0 += 32) {
;                 float wv[32];
; #pragma unroll
;                 for (int q = 0; q < 32; ++q) wv[q] = wm[(size_t)(k0 + q) * 6144];
;                 asm volatile("" ::: "memory");
; #pragma unroll
;                 for (int q = 0; q < 32; ++q) { const int k = k0 + q; const float w = wv[q];
;                     a0 += scr[k] * w; a1 += scr[1024 + k] * w; a2 += scr[2048 + k] * w; a3 += scr[3072 + k] * w; a4 += scr[4096 + k] * w; }
;             }
;             __syncthreads();
;             LAS float* part = scr + 5120;
;             part[(ks * 5 + 0) * 64 + (tid & 63)] = a0; part[(ks * 5 + 1) * 64 + (tid & 63)] = a1; part[(ks * 5 + 2) * 64 + (tid & 63)] = a2;
;             part[(ks * 5 + 3) * 64 + (tid & 63)] = a3; part[(ks * 5 + 4) * 64 + (tid & 63)] = a4;
;             __syncthreads();
;             if (tid < 320) { const int r = tid >> 6, cc = tid & 63; float s = p.b_mod[l * 6144 + cb * 64 + cc];
; #pragma unroll
;                 for (int q = 0; q < 8; ++q) s += part[(q * 5 + r) * 64 + cc];
;                 ((float*)(p.ws + OFF_MOD))[(size_t)(l * 5 + r) * 6144 + cb * 64 + cc] = s; }
	v_fmac_f32_e32 v94, v54, v154
	v_fmac_f32_e32 v95, v58, v154
	v_fmac_f32_e32 v96, v2, v154
	v_fmac_f32_e32 v62, v98, v154
	v_fmac_f32_e32 v63, v102, v154
	v_fmac_f32_e32 v94, v55, v155
	v_fmac_f32_e32 v95, v59, v155
	v_fmac_f32_e32 v96, v3, v155
	v_fmac_f32_e32 v62, v99, v155
	v_fmac_f32_e32 v63, v103, v155
	v_fmac_f32_e32 v94, v56, v156
	v_fmac_f32_e32 v95, v60, v156
	v_fmac_f32_e32 v96, v4, v156
	v_fmac_f32_e32 v62, v100, v156
	v_fmac_f32_e32 v63, v104, v156
	v_fmac_f32_e32 v94, v57, v157
	v_fmac_f32_e32 v95, v61, v157
	v_fmac_f32_e32 v96, v5, v157
	v_fmac_f32_e32 v62, v101, v157
	v_fmac_f32_e32 v63, v105, v157
	ds_read_b128 v[54:57], v116 offset:432
	ds_read_b128 v[58:61], v116 offset:4528
	ds_read_b128 v[2:5], v116 offset:8624
	ds_read_b128 v[98:101], v116 offset:12720
	ds_read_b128 v[102:105], v116 offset:16816
	s_waitcnt vmcnt(16) lgkmcnt(5)
	v_fmac_f32_e32 v94, v78, v158
	v_fmac_f32_e32 v95, v82, v158
	v_fmac_f32_e32 v96, v86, v158
	v_fmac_f32_e32 v62, v90, v158
	v_fmac_f32_e32 v63, v50, v158
	v_fmac_f32_e32 v94, v79, v159
	v_fmac_f32_e32 v95, v83, v159
	v_fmac_f32_e32 v96, v87, v159
	v_fmac_f32_e32 v62, v91, v159
	v_fmac_f32_e32 v63, v51, v159
	v_fmac_f32_e32 v94, v80, v160
	v_fmac_f32_e32 v95, v84, v160
	v_fmac_f32_e32 v96, v88, v160
	v_fmac_f32_e32 v62, v92, v160
	v_fmac_f32_e32 v63, v52, v160
	v_fmac_f32_e32 v94, v81, v161
	v_fmac_f32_e32 v95, v85, v161
	v_fmac_f32_e32 v96, v89, v161
	v_fmac_f32_e32 v62, v93, v161
	v_fmac_f32_e32 v63, v53, v161
	ds_read_b128 v[78:81], v116 offset:448
	ds_read_b128 v[82:85], v116 offset:4544
	ds_read_b128 v[86:89], v116 offset:8640
	ds_read_b128 v[90:93], v116 offset:12736
	ds_read_b128 v[50:53], v116 offset:16832
	s_waitcnt lgkmcnt(5)
	v_fmac_f32_e32 v94, v54, v162
	v_fmac_f32_e32 v95, v58, v162
	v_fmac_f32_e32 v96, v2, v162
	v_fmac_f32_e32 v62, v98, v162
	v_fmac_f32_e32 v63, v102, v162
	v_fmac_f32_e32 v94, v55, v163
	v_fmac_f32_e32 v95, v59, v163
	v_fmac_f32_e32 v96, v3, v163
	v_fmac_f32_e32 v62, v99, v163
	v_fmac_f32_e32 v63, v103, v163
	v_fmac_f32_e32 v94, v56, v164
	v_fmac_f32_e32 v95, v60, v164
	v_fmac_f32_e32 v96, v4, v164
	v_fmac_f32_e32 v62, v100, v164
	v_fmac_f32_e32 v63, v104, v164
	v_fmac_f32_e32 v94, v57, v165
	v_fmac_f32_e32 v95, v61, v165
	v_fmac_f32_e32 v96, v5, v165
	v_fmac_f32_e32 v62, v101, v165
	v_fmac_f32_e32 v63, v105, v165
	ds_read_b128 v[54:57], v116 offset:464
	ds_read_b128 v[58:61], v116 offset:4560
	ds_read_b128 v[2:5], v116 offset:8656
	ds_read_b128 v[98:101], v116 offset:12752
	ds_read_b128 v[102:105], v116 offset:16848
	s_waitcnt vmcnt(8) lgkmcnt(5)
	v_fmac_f32_e32 v94, v78, v166
	v_fmac_f32_e32 v95, v82, v166
	v_fmac_f32_e32 v96, v86, v166
	v_fmac_f32_e32 v62, v90, v166
	v_fmac_f32_e32 v63, v50, v166
	v_fmac_f32_e32 v94, v79, v167
	v_fmac_f32_e32 v95, v83, v167
	v_fmac_f32_e32 v96, v87, v167
	v_fmac_f32_e32 v62, v91, v167
	v_fmac_f32_e32 v63, v51, v167
	v_fmac_f32_e32 v94, v80, v168
	v_fmac_f32_e32 v95, v84, v168
	v_fmac_f32_e32 v96, v88, v168
	v_fmac_f32_e32 v62, v92, v168
	v_fmac_f32_e32 v63, v52, v168
	v_fmac_f32_e32 v94, v81, v169
	v_fmac_f32_e32 v95, v85, v169
	v_fmac_f32_e32 v96, v89, v169
	v_fmac_f32_e32 v62, v93, v169
	v_fmac_f32_e32 v63, v53, v169
	ds_read_b128 v[78:81], v116 offset:480
	ds_read_b128 v[82:85], v116 offset:4576
	ds_read_b128 v[86:89], v116 offset:8672
	ds_read_b128 v[90:93], v116 offset:12768
	ds_read_b128 v[50:53], v116 offset:16864
	s_waitcnt lgkmcnt(5)
	v_fmac_f32_e32 v94, v54, v170
	v_fmac_f32_e32 v95, v58, v170
	v_fmac_f32_e32 v96, v2, v170
	v_fmac_f32_e32 v62, v98, v170
	v_fmac_f32_e32 v63, v102, v170
	v_fmac_f32_e32 v94, v55, v171
	v_fmac_f32_e32 v95, v59, v171
	v_fmac_f32_e32 v96, v3, v171
	v_fmac_f32_e32 v62, v99, v171
	v_fmac_f32_e32 v63, v103, v171
	v_fmac_f32_e32 v94, v56, v172
	v_fmac_f32_e32 v95, v60, v172
	v_fmac_f32_e32 v96, v4, v172
	v_fmac_f32_e32 v62, v100, v172
	v_fmac_f32_e32 v63, v104, v172
	v_fmac_f32_e32 v94, v57, v173
	v_fmac_f32_e32 v95, v61, v173
	v_fmac_f32_e32 v96, v5, v173
	v_fmac_f32_e32 v62, v101, v173
	v_fmac_f32_e32 v63, v105, v173
	ds_read_b128 v[54:57], v116 offset:496
	ds_read_b128 v[58:61], v116 offset:4592
	ds_read_b128 v[2:5], v116 offset:8688
	ds_read_b128 v[98:101], v116 offset:12784
	ds_read_b128 v[102:105], v116 offset:16880
	s_waitcnt vmcnt(0) lgkmcnt(5)
	v_fmac_f32_e32 v94, v78, v64
	v_fmac_f32_e32 v95, v82, v64
	v_fmac_f32_e32 v96, v86, v64
	v_fmac_f32_e32 v62, v90, v64
	v_fmac_f32_e32 v63, v50, v64
	v_fmac_f32_e32 v94, v79, v66
	v_fmac_f32_e32 v95, v83, v66
	v_fmac_f32_e32 v96, v87, v66
	v_fmac_f32_e32 v62, v91, v66
	v_fmac_f32_e32 v63, v51, v66
	v_fmac_f32_e32 v94, v80, v67
	v_fmac_f32_e32 v95, v84, v67
	v_fmac_f32_e32 v96, v88, v67
	v_fmac_f32_e32 v62, v92, v67
	v_fmac_f32_e32 v63, v52, v67
	v_fmac_f32_e32 v94, v81, v68
	v_fmac_f32_e32 v95, v85, v68
	v_fmac_f32_e32 v96, v89, v68
	v_fmac_f32_e32 v62, v93, v68
	v_fmac_f32_e32 v63, v53, v68
	s_waitcnt lgkmcnt(0)
	v_fmac_f32_e32 v94, v54, v70
	v_fmac_f32_e32 v95, v58, v70
	v_fmac_f32_e32 v96, v2, v70
	v_fmac_f32_e32 v62, v98, v70
	v_fmac_f32_e32 v63, v102, v70
	v_fmac_f32_e32 v94, v55, v72
	v_fmac_f32_e32 v95, v59, v72
	v_fmac_f32_e32 v96, v3, v72
	v_fmac_f32_e32 v62, v99, v72
	v_fmac_f32_e32 v63, v103, v72
	v_fmac_f32_e32 v94, v56, v74
	v_fmac_f32_e32 v95, v60, v74
	v_fmac_f32_e32 v96, v4, v74
	v_fmac_f32_e32 v62, v100, v74
	v_fmac_f32_e32 v63, v104, v74
	v_fmac_f32_e32 v94, v57, v76
	v_fmac_f32_e32 v95, v61, v76
	v_fmac_f32_e32 v96, v5, v76
	v_fmac_f32_e32 v62, v101, v76
	v_fmac_f32_e32 v63, v105, v76
	v_mov_b32_e32 v83, v94
	v_mov_b32_e32 v55, v95
	v_mov_b32_e32 v54, v96
	v_mov_b32_e32 v53, v62
	v_mov_b32_e32 v52, v63
	s_barrier
	ds_write2st64_b32 v30, v83, v55 offset0:80 offset1:81
	ds_write2st64_b32 v30, v54, v53 offset0:82 offset1:83
	ds_write_b32 v30, v52 offset:21504
	s_waitcnt lgkmcnt(0)
	s_barrier
	s_and_saveexec_b64 s[4:5], s[42:43]
	s_cbranch_execz .LBB0_664
	s_and_b64 s[6:7], s[0:1], exec
	s_cselect_b32 s6, 0x1800, 0
	s_add_i32 s6, s2, s6
	v_or_b32_e32 v96, s6, v28
	v_lshl_add_u64 v[2:3], v[96:97], 2, v[16:17]
	flat_load_dword v4, v[2:3]
	ds_read2st64_b32 v[2:3], v117 offset0:80 offset1:85
	s_and_b64 s[0:1], s[0:1], exec
	s_cselect_b32 s0, 5, 0
	v_lshlrev_b32_e32 v96, 2, v28
	s_waitcnt vmcnt(0) lgkmcnt(0)
	v_add_f32_e32 v2, v4, v2
	v_add_f32_e32 v4, v2, v3
	ds_read2st64_b32 v[2:3], v117 offset0:90 offset1:95
	s_waitcnt lgkmcnt(0)
	v_add_f32_e32 v2, v4, v2
	v_add_f32_e32 v4, v2, v3
	ds_read2st64_b32 v[2:3], v117 offset0:100 offset1:105
	s_waitcnt lgkmcnt(0)
	v_add_f32_e32 v2, v4, v2
	v_add_f32_e32 v4, v2, v3
	ds_read2st64_b32 v[2:3], v117 offset0:110 offset1:115
	s_waitcnt lgkmcnt(0)
	v_add_f32_e32 v2, v4, v2
	v_add_f32_e32 v4, v2, v3
	v_add_u32_e32 v2, s0, v29
	v_mad_i64_i32 v[2:3], s[0:1], v2, s28, v[24:25]
	v_lshl_add_u64 v[2:3], s[2:3], 2, v[2:3]
	v_lshl_add_u64 v[2:3], v[2:3], 0, v[96:97]
	flat_store_dword v[2:3], v4
